# grid barrier: non-leader workgroups poll the global release generation directly (one hop less)
# baseline (speedup 1.0000x reference)
.LBB0_101:
	s_or_b64 exec, exec, s[8:9]
	v_cvt_f32_u32_e32 v4, v2
	s_waitcnt vmcnt(0)
	v_readfirstlane_b32 s3, v3
	v_sub_u32_e32 v3, 0, v2
	v_rcp_iflag_f32_e32 v4, v4
	v_add_u32_e32 v5, s3, v1
	v_mul_f32_e32 v4, 0x4f7ffffe, v4
	v_cvt_u32_f32_e32 v4, v4
	v_mul_lo_u32 v1, v3, v4
	v_mul_hi_u32 v1, v4, v1
	v_add_u32_e32 v1, v4, v1
	v_mul_hi_u32 v1, v5, v1
	v_mul_lo_u32 v3, v1, v2
	v_sub_u32_e32 v3, v5, v3
	v_add_u32_e32 v4, 1, v1
	v_sub_u32_e32 v6, v3, v2
	v_cmp_ge_u32_e32 vcc, v3, v2
	s_nop 1
	v_cndmask_b32_e32 v1, v1, v4, vcc
	v_cndmask_b32_e32 v3, v3, v6, vcc
	v_add_u32_e32 v4, 1, v1
	v_cmp_ge_u32_e32 vcc, v3, v2
	v_add_u32_e32 v3, 1, v5
	s_nop 0
	v_cndmask_b32_e32 v1, v1, v4, vcc
	v_mul_lo_u32 v4, v2, v1
	v_add_u32_e32 v2, v4, v2
	v_cmp_ne_u32_e32 vcc, v3, v2
	s_and_saveexec_b64 s[8:9], vcc
	s_xor_b64 s[8:9], exec, s[8:9]
	s_cbranch_execz .LBB0_115
	s_waitcnt lgkmcnt(0)
	v_mov_b32_e32 v0, 0
	buffer_inv sc1
	s_mov_b64 s[98:99], s[62:63]
	s_add_u32 s98, s98, 0x7500
	s_addc_u32 s99, s99, 0
	v_mov_b32_e32 v1, 0
	global_load_dword v2, v0, s[98:99] sc1
	s_waitcnt vmcnt(0)
	v_cmp_eq_u32_e32 vcc, v2, v1
	s_and_saveexec_b64 s[10:11], vcc
	s_cbranch_execz .LBB0_114
	s_mov_b32 s3, 1
	s_mov_b64 s[38:39], 0
	s_branch .LBB0_105

.LBB0_109:
	global_load_dword v2, v0, s[98:99] sc1
	s_add_i32 s3, s3, 1
	s_mov_b64 s[44:45], -1
	s_waitcnt vmcnt(0)
	v_cmp_ne_u32_e32 vcc, v2, v1
	s_orn2_b64 s[42:43], vcc, exec
	s_branch .LBB0_104

.LBB0_635:
	s_or_b64 exec, exec, s[8:9]
	v_cvt_f32_u32_e32 v4, v2
	s_waitcnt vmcnt(0)
	v_readfirstlane_b32 s8, v3
	v_sub_u32_e32 v3, 0, v2
	v_rcp_iflag_f32_e32 v4, v4
	v_add_u32_e32 v5, s8, v1
	v_mul_f32_e32 v4, 0x4f7ffffe, v4
	v_cvt_u32_f32_e32 v4, v4
	v_mul_lo_u32 v1, v3, v4
	v_mul_hi_u32 v1, v4, v1
	v_add_u32_e32 v1, v4, v1
	v_mul_hi_u32 v1, v5, v1
	v_mul_lo_u32 v3, v1, v2
	v_sub_u32_e32 v3, v5, v3
	v_add_u32_e32 v4, 1, v1
	v_cmp_ge_u32_e32 vcc, v3, v2
	s_nop 1
	v_cndmask_b32_e32 v1, v1, v4, vcc
	v_sub_u32_e32 v4, v3, v2
	v_cndmask_b32_e32 v3, v3, v4, vcc
	v_add_u32_e32 v4, 1, v1
	v_cmp_ge_u32_e32 vcc, v3, v2
	v_add_u32_e32 v3, 1, v5
	s_nop 0
	v_cndmask_b32_e32 v1, v1, v4, vcc
	v_mul_lo_u32 v4, v2, v1
	v_add_u32_e32 v2, v4, v2
	v_cmp_ne_u32_e32 vcc, v3, v2
	s_and_saveexec_b64 s[8:9], vcc
	s_xor_b64 s[8:9], exec, s[8:9]
	s_cbranch_execz .LBB0_649
	s_waitcnt lgkmcnt(0)
	v_mov_b32_e32 v0, 0
	buffer_inv sc1
	v_readlane_b32 s98, v244, 25
	v_readlane_b32 s99, v244, 26
	s_nop 3
	s_add_u32 s98, s98, 0x7500
	s_addc_u32 s99, s99, 0
	v_mov_b32_e32 v1, 1
	global_load_dword v2, v0, s[98:99] sc1
	s_waitcnt vmcnt(0)
	v_cmp_eq_u32_e32 vcc, v2, v1
	s_and_saveexec_b64 s[10:11], vcc
	s_cbranch_execz .LBB0_648
	s_mov_b32 s20, 1
	s_mov_b64 s[38:39], 0
	s_branch .LBB0_639

.LBB0_643:
	global_load_dword v2, v0, s[98:99] sc1
	s_add_i32 s20, s20, 1
	s_mov_b64 s[44:45], -1
	s_waitcnt vmcnt(0)
	v_cmp_ne_u32_e32 vcc, v2, v1
	s_orn2_b64 s[42:43], vcc, exec
	s_branch .LBB0_638

.LBB0_722:
	s_or_b64 exec, exec, s[8:9]
	v_cvt_f32_u32_e32 v4, v2
	s_waitcnt vmcnt(0)
	v_readfirstlane_b32 s8, v3
	v_sub_u32_e32 v3, 0, v2
	v_rcp_iflag_f32_e32 v4, v4
	v_add_u32_e32 v5, s8, v1
	v_mul_f32_e32 v4, 0x4f7ffffe, v4
	v_cvt_u32_f32_e32 v4, v4
	v_mul_lo_u32 v1, v3, v4
	v_mul_hi_u32 v1, v4, v1
	v_add_u32_e32 v1, v4, v1
	v_mul_hi_u32 v1, v5, v1
	v_mul_lo_u32 v3, v1, v2
	v_sub_u32_e32 v3, v5, v3
	v_add_u32_e32 v4, 1, v1
	v_cmp_ge_u32_e32 vcc, v3, v2
	s_nop 1
	v_cndmask_b32_e32 v1, v1, v4, vcc
	v_sub_u32_e32 v4, v3, v2
	v_cndmask_b32_e32 v3, v3, v4, vcc
	v_add_u32_e32 v4, 1, v1
	v_cmp_ge_u32_e32 vcc, v3, v2
	v_add_u32_e32 v3, 1, v5
	s_nop 0
	v_cndmask_b32_e32 v1, v1, v4, vcc
	v_mul_lo_u32 v4, v2, v1
	v_add_u32_e32 v2, v4, v2
	v_cmp_ne_u32_e32 vcc, v3, v2
	s_and_saveexec_b64 s[8:9], vcc
	s_xor_b64 s[8:9], exec, s[8:9]
	s_cbranch_execz .LBB0_736
	s_waitcnt lgkmcnt(0)
	v_mov_b32_e32 v0, 0
	buffer_inv sc1
	v_readlane_b32 s98, v244, 25
	v_readlane_b32 s99, v244, 26
	s_nop 3
	s_add_u32 s98, s98, 0x7500
	s_addc_u32 s99, s99, 0
	v_mov_b32_e32 v1, 2
	global_load_dword v2, v0, s[98:99] sc1
	s_waitcnt vmcnt(0)
	v_cmp_eq_u32_e32 vcc, v2, v1
	s_and_saveexec_b64 s[10:11], vcc
	s_cbranch_execz .LBB0_735
	s_mov_b32 s20, 1
	s_mov_b64 s[38:39], 0
	s_branch .LBB0_726

.LBB0_809:
	s_or_b64 exec, exec, s[8:9]
	v_cvt_f32_u32_e32 v4, v2
	s_waitcnt vmcnt(0)
	v_readfirstlane_b32 s8, v3
	v_sub_u32_e32 v3, 0, v2
	v_rcp_iflag_f32_e32 v4, v4
	v_add_u32_e32 v5, s8, v1
	v_mul_f32_e32 v4, 0x4f7ffffe, v4
	v_cvt_u32_f32_e32 v4, v4
	v_mul_lo_u32 v1, v3, v4
	v_mul_hi_u32 v1, v4, v1
	v_add_u32_e32 v1, v4, v1
	v_mul_hi_u32 v1, v5, v1
	v_mul_lo_u32 v3, v1, v2
	v_sub_u32_e32 v3, v5, v3
	v_add_u32_e32 v4, 1, v1
	v_cmp_ge_u32_e32 vcc, v3, v2
	s_nop 1
	v_cndmask_b32_e32 v1, v1, v4, vcc
	v_sub_u32_e32 v4, v3, v2
	v_cndmask_b32_e32 v3, v3, v4, vcc
	v_add_u32_e32 v4, 1, v1
	v_cmp_ge_u32_e32 vcc, v3, v2
	v_add_u32_e32 v3, 1, v5
	s_nop 0
	v_cndmask_b32_e32 v1, v1, v4, vcc
	v_mul_lo_u32 v4, v2, v1
	v_add_u32_e32 v2, v4, v2
	v_cmp_ne_u32_e32 vcc, v3, v2
	s_and_saveexec_b64 s[8:9], vcc
	s_xor_b64 s[8:9], exec, s[8:9]
	s_cbranch_execz .LBB0_823
	s_waitcnt lgkmcnt(0)
	v_mov_b32_e32 v0, 0
	buffer_inv sc1
	v_readlane_b32 s98, v244, 25
	v_readlane_b32 s99, v244, 26
	s_nop 3
	s_add_u32 s98, s98, 0x7500
	s_addc_u32 s99, s99, 0
	v_mov_b32_e32 v1, 3
	global_load_dword v2, v0, s[98:99] sc1
	s_waitcnt vmcnt(0)
	v_cmp_eq_u32_e32 vcc, v2, v1
	s_and_saveexec_b64 s[10:11], vcc
	s_cbranch_execz .LBB0_822
	s_mov_b32 s20, 1
	s_mov_b64 s[14:15], 0
	s_branch .LBB0_813

.LBB0_817:
	global_load_dword v2, v0, s[98:99] sc1
	s_add_i32 s20, s20, 1
	s_mov_b64 s[42:43], -1
	s_waitcnt vmcnt(0)
	v_cmp_ne_u32_e32 vcc, v2, v1
	s_orn2_b64 s[40:41], vcc, exec
	s_branch .LBB0_812

.LBB0_877:
	s_or_b64 exec, exec, s[8:9]
	v_cvt_f32_u32_e32 v4, v2
	s_waitcnt vmcnt(0)
	v_readfirstlane_b32 s8, v3
	v_sub_u32_e32 v3, 0, v2
	v_rcp_iflag_f32_e32 v4, v4
	v_add_u32_e32 v5, s8, v1
	v_mul_f32_e32 v4, 0x4f7ffffe, v4
	v_cvt_u32_f32_e32 v4, v4
	v_mul_lo_u32 v1, v3, v4
	v_mul_hi_u32 v1, v4, v1
	v_add_u32_e32 v1, v4, v1
	v_mul_hi_u32 v1, v5, v1
	v_mul_lo_u32 v3, v1, v2
	v_sub_u32_e32 v3, v5, v3
	v_add_u32_e32 v4, 1, v1
	v_cmp_ge_u32_e32 vcc, v3, v2
	s_nop 1
	v_cndmask_b32_e32 v1, v1, v4, vcc
	v_sub_u32_e32 v4, v3, v2
	v_cndmask_b32_e32 v3, v3, v4, vcc
	v_add_u32_e32 v4, 1, v1
	v_cmp_ge_u32_e32 vcc, v3, v2
	v_add_u32_e32 v3, 1, v5
	s_nop 0
	v_cndmask_b32_e32 v1, v1, v4, vcc
	v_mul_lo_u32 v4, v2, v1
	v_add_u32_e32 v2, v4, v2
	v_cmp_ne_u32_e32 vcc, v3, v2
	s_and_saveexec_b64 s[8:9], vcc
	s_xor_b64 s[8:9], exec, s[8:9]
	s_cbranch_execz .LBB0_891
	s_waitcnt lgkmcnt(0)
	v_mov_b32_e32 v0, 0
	buffer_inv sc1
	v_readlane_b32 s98, v244, 25
	v_readlane_b32 s99, v244, 26
	s_nop 3
	s_add_u32 s98, s98, 0x7500
	s_addc_u32 s99, s99, 0
	v_mov_b32_e32 v1, 4
	global_load_dword v2, v0, s[98:99] sc1
	s_waitcnt vmcnt(0)
	v_cmp_eq_u32_e32 vcc, v2, v1
	s_and_saveexec_b64 s[10:11], vcc
	s_cbranch_execz .LBB0_890
	s_mov_b32 s20, 1
	s_mov_b64 s[14:15], 0
	s_branch .LBB0_881

.LBB0_952:
	s_or_b64 exec, exec, s[8:9]
	v_cvt_f32_u32_e32 v4, v2
	s_waitcnt vmcnt(0)
	v_readfirstlane_b32 s8, v3
	v_sub_u32_e32 v3, 0, v2
	v_rcp_iflag_f32_e32 v4, v4
	v_add_u32_e32 v5, s8, v1
	v_mul_f32_e32 v4, 0x4f7ffffe, v4
	v_cvt_u32_f32_e32 v4, v4
	v_mul_lo_u32 v1, v3, v4
	v_mul_hi_u32 v1, v4, v1
	v_add_u32_e32 v1, v4, v1
	v_mul_hi_u32 v1, v5, v1
	v_mul_lo_u32 v3, v1, v2
	v_sub_u32_e32 v3, v5, v3
	v_add_u32_e32 v4, 1, v1
	v_cmp_ge_u32_e32 vcc, v3, v2
	s_nop 1
	v_cndmask_b32_e32 v1, v1, v4, vcc
	v_sub_u32_e32 v4, v3, v2
	v_cndmask_b32_e32 v3, v3, v4, vcc
	v_add_u32_e32 v4, 1, v1
	v_cmp_ge_u32_e32 vcc, v3, v2
	v_add_u32_e32 v3, 1, v5
	s_nop 0
	v_cndmask_b32_e32 v1, v1, v4, vcc
	v_mul_lo_u32 v4, v2, v1
	v_add_u32_e32 v2, v4, v2
	v_cmp_ne_u32_e32 vcc, v3, v2
	s_and_saveexec_b64 s[8:9], vcc
	s_xor_b64 s[8:9], exec, s[8:9]
	s_cbranch_execz .LBB0_966
	s_waitcnt lgkmcnt(0)
	v_mov_b32_e32 v0, 0
	buffer_inv sc1
	v_readlane_b32 s98, v244, 25
	v_readlane_b32 s99, v244, 26
	s_nop 3
	s_add_u32 s98, s98, 0x7500
	s_addc_u32 s99, s99, 0
	v_mov_b32_e32 v1, 5
	global_load_dword v2, v0, s[98:99] sc1
	s_waitcnt vmcnt(0)
	v_cmp_eq_u32_e32 vcc, v2, v1
	s_and_saveexec_b64 s[10:11], vcc
	s_cbranch_execz .LBB0_965
	s_mov_b32 s15, 1
	s_mov_b64 s[38:39], 0
	s_branch .LBB0_956

.LBB0_960:
	global_load_dword v2, v0, s[98:99] sc1
	s_add_i32 s15, s15, 1
	s_mov_b64 s[48:49], -1
	s_waitcnt vmcnt(0)
	v_cmp_ne_u32_e32 vcc, v2, v1
	s_orn2_b64 s[46:47], vcc, exec
	s_branch .LBB0_955

.LBB0_1019:
	s_or_b64 exec, exec, s[4:5]
	v_cvt_f32_u32_e32 v4, v2
	s_waitcnt vmcnt(0)
	v_readfirstlane_b32 s4, v3
	v_sub_u32_e32 v3, 0, v2
	v_rcp_iflag_f32_e32 v4, v4
	v_add_u32_e32 v5, s4, v1
	v_mul_f32_e32 v4, 0x4f7ffffe, v4
	v_cvt_u32_f32_e32 v4, v4
	v_mul_lo_u32 v1, v3, v4
	v_mul_hi_u32 v1, v4, v1
	v_add_u32_e32 v1, v4, v1
	v_mul_hi_u32 v1, v5, v1
	v_mul_lo_u32 v3, v1, v2
	v_sub_u32_e32 v3, v5, v3
	v_add_u32_e32 v4, 1, v1
	v_cmp_ge_u32_e32 vcc, v3, v2
	s_nop 1
	v_cndmask_b32_e32 v1, v1, v4, vcc
	v_sub_u32_e32 v4, v3, v2
	v_cndmask_b32_e32 v3, v3, v4, vcc
	v_add_u32_e32 v4, 1, v1
	v_cmp_ge_u32_e32 vcc, v3, v2
	v_add_u32_e32 v3, 1, v5
	s_nop 0
	v_cndmask_b32_e32 v1, v1, v4, vcc
	v_mul_lo_u32 v4, v2, v1
	v_add_u32_e32 v2, v4, v2
	v_cmp_ne_u32_e32 vcc, v3, v2
	s_and_saveexec_b64 s[4:5], vcc
	s_xor_b64 s[4:5], exec, s[4:5]
	s_cbranch_execz .LBB0_1033
	s_waitcnt lgkmcnt(0)
	v_mov_b32_e32 v0, 0
	buffer_inv sc1
	v_readlane_b32 s98, v244, 25
	v_readlane_b32 s99, v244, 26
	s_nop 3
	s_add_u32 s98, s98, 0x7500
	s_addc_u32 s99, s99, 0
	v_mov_b32_e32 v1, 6
	global_load_dword v2, v0, s[98:99] sc1
	s_waitcnt vmcnt(0)
	v_cmp_eq_u32_e32 vcc, v2, v1
	s_and_saveexec_b64 s[6:7], vcc
	s_cbranch_execz .LBB0_1032
	s_mov_b32 s15, 1
	s_mov_b64 s[8:9], 0
	s_branch .LBB0_1023

.LBB0_1027:
	global_load_dword v2, v0, s[98:99] sc1
	s_add_i32 s15, s15, 1
	s_mov_b64 s[44:45], -1
	s_waitcnt vmcnt(0)
	v_cmp_ne_u32_e32 vcc, v2, v1
	s_orn2_b64 s[38:39], vcc, exec
	s_branch .LBB0_1022

.LBB0_1128:
	s_or_b64 exec, exec, s[4:5]
	v_cvt_f32_u32_e32 v4, v2
	s_waitcnt vmcnt(0)
	v_readfirstlane_b32 s4, v3
	v_sub_u32_e32 v3, 0, v2
	v_rcp_iflag_f32_e32 v4, v4
	v_add_u32_e32 v5, s4, v1
	v_mul_f32_e32 v4, 0x4f7ffffe, v4
	v_cvt_u32_f32_e32 v4, v4
	v_mul_lo_u32 v1, v3, v4
	v_mul_hi_u32 v1, v4, v1
	v_add_u32_e32 v1, v4, v1
	v_mul_hi_u32 v1, v5, v1
	v_mul_lo_u32 v3, v1, v2
	v_sub_u32_e32 v3, v5, v3
	v_add_u32_e32 v4, 1, v1
	v_cmp_ge_u32_e32 vcc, v3, v2
	s_nop 1
	v_cndmask_b32_e32 v1, v1, v4, vcc
	v_sub_u32_e32 v4, v3, v2
	v_cndmask_b32_e32 v3, v3, v4, vcc
	v_add_u32_e32 v4, 1, v1
	v_cmp_ge_u32_e32 vcc, v3, v2
	v_add_u32_e32 v3, 1, v5
	s_nop 0
	v_cndmask_b32_e32 v1, v1, v4, vcc
	v_mul_lo_u32 v4, v2, v1
	v_add_u32_e32 v2, v4, v2
	v_cmp_ne_u32_e32 vcc, v3, v2
	s_and_saveexec_b64 s[4:5], vcc
	s_xor_b64 s[4:5], exec, s[4:5]
	s_cbranch_execz .LBB0_1142
	s_waitcnt lgkmcnt(0)
	v_mov_b32_e32 v0, 0
	buffer_inv sc1
	v_readlane_b32 s98, v244, 25
	v_readlane_b32 s99, v244, 26
	s_nop 3
	s_add_u32 s98, s98, 0x7500
	s_addc_u32 s99, s99, 0
	v_mov_b32_e32 v1, 7
	global_load_dword v2, v0, s[98:99] sc1
	s_waitcnt vmcnt(0)
	v_cmp_eq_u32_e32 vcc, v2, v1
	s_and_saveexec_b64 s[6:7], vcc
	s_cbranch_execz .LBB0_1141
	s_mov_b32 s15, 1
	s_mov_b64 s[8:9], 0
	s_branch .LBB0_1132

.LBB0_1136:
	global_load_dword v2, v0, s[98:99] sc1
	s_add_i32 s15, s15, 1
	s_mov_b64 s[44:45], -1
	s_waitcnt vmcnt(0)
	v_cmp_ne_u32_e32 vcc, v2, v1
	s_orn2_b64 s[40:41], vcc, exec
	s_branch .LBB0_1131

.LBB0_1262:
	s_or_b64 exec, exec, s[4:5]
	v_cvt_f32_u32_e32 v4, v2
	s_waitcnt vmcnt(0)
	v_readfirstlane_b32 s4, v3
	v_sub_u32_e32 v3, 0, v2
	v_rcp_iflag_f32_e32 v4, v4
	v_add_u32_e32 v5, s4, v1
	v_mul_f32_e32 v4, 0x4f7ffffe, v4
	v_cvt_u32_f32_e32 v4, v4
	v_mul_lo_u32 v1, v3, v4
	v_mul_hi_u32 v1, v4, v1
	v_add_u32_e32 v1, v4, v1
	v_mul_hi_u32 v1, v5, v1
	v_mul_lo_u32 v3, v1, v2
	v_sub_u32_e32 v3, v5, v3
	v_add_u32_e32 v4, 1, v1
	v_cmp_ge_u32_e32 vcc, v3, v2
	s_nop 1
	v_cndmask_b32_e32 v1, v1, v4, vcc
	v_sub_u32_e32 v4, v3, v2
	v_cndmask_b32_e32 v3, v3, v4, vcc
	v_add_u32_e32 v4, 1, v1
	v_cmp_ge_u32_e32 vcc, v3, v2
	v_add_u32_e32 v3, 1, v5
	s_nop 0
	v_cndmask_b32_e32 v1, v1, v4, vcc
	v_mul_lo_u32 v4, v2, v1
	v_add_u32_e32 v2, v4, v2
	v_cmp_ne_u32_e32 vcc, v3, v2
	s_and_saveexec_b64 s[4:5], vcc
	s_xor_b64 s[4:5], exec, s[4:5]
	s_cbranch_execz .LBB0_1276
	s_waitcnt lgkmcnt(0)
	v_mov_b32_e32 v0, 0
	buffer_inv sc1
	v_readlane_b32 s98, v244, 25
	v_readlane_b32 s99, v244, 26
	s_nop 3
	s_add_u32 s98, s98, 0x7500
	s_addc_u32 s99, s99, 0
	v_mov_b32_e32 v1, 8
	global_load_dword v2, v0, s[98:99] sc1
	s_waitcnt vmcnt(0)
	v_cmp_eq_u32_e32 vcc, v2, v1
	s_and_saveexec_b64 s[6:7], vcc
	s_cbranch_execz .LBB0_1275
	s_mov_b32 s15, 1
	s_mov_b64 s[8:9], 0
	s_branch .LBB0_1266

.LBB0_1329:
	s_or_b64 exec, exec, s[4:5]
	v_cvt_f32_u32_e32 v4, v2
	s_waitcnt vmcnt(0)
	v_readfirstlane_b32 s4, v3
	v_sub_u32_e32 v3, 0, v2
	v_rcp_iflag_f32_e32 v4, v4
	v_add_u32_e32 v5, s4, v1
	v_mul_f32_e32 v4, 0x4f7ffffe, v4
	v_cvt_u32_f32_e32 v4, v4
	v_mul_lo_u32 v1, v3, v4
	v_mul_hi_u32 v1, v4, v1
	v_add_u32_e32 v1, v4, v1
	v_mul_hi_u32 v1, v5, v1
	v_mul_lo_u32 v3, v1, v2
	v_sub_u32_e32 v3, v5, v3
	v_add_u32_e32 v4, 1, v1
	v_cmp_ge_u32_e32 vcc, v3, v2
	s_nop 1
	v_cndmask_b32_e32 v1, v1, v4, vcc
	v_sub_u32_e32 v4, v3, v2
	v_cndmask_b32_e32 v3, v3, v4, vcc
	v_add_u32_e32 v4, 1, v1
	v_cmp_ge_u32_e32 vcc, v3, v2
	v_add_u32_e32 v3, 1, v5
	s_nop 0
	v_cndmask_b32_e32 v1, v1, v4, vcc
	v_mul_lo_u32 v4, v2, v1
	v_add_u32_e32 v2, v4, v2
	v_cmp_ne_u32_e32 vcc, v3, v2
	s_and_saveexec_b64 s[4:5], vcc
	s_xor_b64 s[4:5], exec, s[4:5]
	s_cbranch_execz .LBB0_1343
	s_waitcnt lgkmcnt(0)
	v_mov_b32_e32 v0, 0
	buffer_inv sc1
	v_readlane_b32 s98, v244, 25
	v_readlane_b32 s99, v244, 26
	s_nop 3
	s_add_u32 s98, s98, 0x7500
	s_addc_u32 s99, s99, 0
	v_mov_b32_e32 v1, 9
	global_load_dword v2, v0, s[98:99] sc1
	s_waitcnt vmcnt(0)
	v_cmp_eq_u32_e32 vcc, v2, v1
	s_and_saveexec_b64 s[6:7], vcc
	s_cbranch_execz .LBB0_1342
	s_mov_b32 s15, 1
	s_mov_b64 s[8:9], 0
	s_branch .LBB0_1333

.LBB0_1401:
	s_or_b64 exec, exec, s[4:5]
	v_cvt_f32_u32_e32 v4, v2
	s_waitcnt vmcnt(0)
	v_readfirstlane_b32 s4, v3
	v_sub_u32_e32 v3, 0, v2
	v_rcp_iflag_f32_e32 v4, v4
	v_add_u32_e32 v5, s4, v1
	v_mul_f32_e32 v4, 0x4f7ffffe, v4
	v_cvt_u32_f32_e32 v4, v4
	v_mul_lo_u32 v1, v3, v4
	v_mul_hi_u32 v1, v4, v1
	v_add_u32_e32 v1, v4, v1
	v_mul_hi_u32 v1, v5, v1
	v_mul_lo_u32 v3, v1, v2
	v_sub_u32_e32 v3, v5, v3
	v_add_u32_e32 v4, 1, v1
	v_cmp_ge_u32_e32 vcc, v3, v2
	s_nop 1
	v_cndmask_b32_e32 v1, v1, v4, vcc
	v_sub_u32_e32 v4, v3, v2
	v_cndmask_b32_e32 v3, v3, v4, vcc
	v_add_u32_e32 v4, 1, v1
	v_cmp_ge_u32_e32 vcc, v3, v2
	v_add_u32_e32 v3, 1, v5
	s_nop 0
	v_cndmask_b32_e32 v1, v1, v4, vcc
	v_mul_lo_u32 v4, v2, v1
	v_add_u32_e32 v2, v4, v2
	v_cmp_ne_u32_e32 vcc, v3, v2
	s_and_saveexec_b64 s[4:5], vcc
	s_xor_b64 s[4:5], exec, s[4:5]
	s_cbranch_execz .LBB0_1415
	s_waitcnt lgkmcnt(0)
	v_mov_b32_e32 v0, 0
	buffer_inv sc1
	v_readlane_b32 s98, v244, 25
	v_readlane_b32 s99, v244, 26
	s_nop 3
	s_add_u32 s98, s98, 0x7500
	s_addc_u32 s99, s99, 0
	v_mov_b32_e32 v1, 10
	global_load_dword v2, v0, s[98:99] sc1
	s_waitcnt vmcnt(0)
	v_cmp_eq_u32_e32 vcc, v2, v1
	s_and_saveexec_b64 s[6:7], vcc
	s_cbranch_execz .LBB0_1414
	s_mov_b32 s15, 1
	s_mov_b64 s[8:9], 0
	s_branch .LBB0_1405

.LBB0_1480:
	s_or_b64 exec, exec, s[2:3]
	v_cvt_f32_u32_e32 v4, v2
	s_waitcnt vmcnt(0)
	v_readfirstlane_b32 s2, v3
	v_sub_u32_e32 v3, 0, v2
	v_rcp_iflag_f32_e32 v4, v4
	v_add_u32_e32 v5, s2, v1
	v_mul_f32_e32 v4, 0x4f7ffffe, v4
	v_cvt_u32_f32_e32 v4, v4
	v_mul_lo_u32 v1, v3, v4
	v_mul_hi_u32 v1, v4, v1
	v_add_u32_e32 v1, v4, v1
	v_mul_hi_u32 v1, v5, v1
	v_mul_lo_u32 v3, v1, v2
	v_sub_u32_e32 v3, v5, v3
	v_add_u32_e32 v4, 1, v1
	v_cmp_ge_u32_e32 vcc, v3, v2
	s_nop 1
	v_cndmask_b32_e32 v1, v1, v4, vcc
	v_sub_u32_e32 v4, v3, v2
	v_cndmask_b32_e32 v3, v3, v4, vcc
	v_add_u32_e32 v4, 1, v1
	v_cmp_ge_u32_e32 vcc, v3, v2
	v_add_u32_e32 v3, 1, v5
	s_nop 0
	v_cndmask_b32_e32 v1, v1, v4, vcc
	v_mul_lo_u32 v4, v2, v1
	v_add_u32_e32 v2, v4, v2
	v_cmp_ne_u32_e32 vcc, v3, v2
	s_and_saveexec_b64 s[2:3], vcc
	s_xor_b64 s[2:3], exec, s[2:3]
	s_cbranch_execz .LBB0_1494
	s_waitcnt lgkmcnt(0)
	v_mov_b32_e32 v0, 0
	buffer_inv sc1
	v_readlane_b32 s98, v244, 25
	v_readlane_b32 s99, v244, 26
	s_nop 3
	s_add_u32 s98, s98, 0x7500
	s_addc_u32 s99, s99, 0
	v_mov_b32_e32 v1, 11
	global_load_dword v2, v0, s[98:99] sc1
	s_waitcnt vmcnt(0)
	v_cmp_eq_u32_e32 vcc, v2, v1
	s_and_saveexec_b64 s[4:5], vcc
	s_cbranch_execz .LBB0_1493
	s_mov_b32 s15, 1
	s_mov_b64 s[6:7], 0
	s_branch .LBB0_1484

.LBB0_1488:
	global_load_dword v2, v0, s[98:99] sc1
	s_add_i32 s15, s15, 1
	s_mov_b64 s[12:13], -1
	s_waitcnt vmcnt(0)
	v_cmp_ne_u32_e32 vcc, v2, v1
	s_orn2_b64 s[10:11], vcc, exec
	s_branch .LBB0_1483
